# prompt attention as split-KV inside the workgroup: wave = (row group, key half), independent online softmax per key half, exact merge at unit end; K staged 4 / V 2 tiles ahead
# speedup vs baseline: 1.0794x; 1.0167x over previous
; template<int THRL,bool PART> __device__ __forceinline__ int attn_unit(const bf16*Qb,const bf16*__restrict__ Kh,const bf16*__restrict__ Vh,bf16*Ob,const int NT,const int vlim_in,char*shm,const int s0,const bool primed,const bf16*nKh,const bf16*nVh,bf16*fuseM,const float lam){
;     ...
;   const int lane=tid&63,r32=lane&31,hi=lane>>5; const int wid=__builtin_amdgcn_readfirstlane(tid>>6);
;   const int vlim=(vlim_in<0)?(wid>>1):vlim_in;
;   const bool act=PART?(wid<2):true;
;   const bf16*Qw=Qb+(long)(wid*QBLK)*KP;
;   const unsigned lds0=(unsigned)(uintptr_t)shm;
;   float*wsf=(float*)(shm+LDS_WS)+wid*64;
;   const bf16*ksrc=Kh+(long)lane*KP+wid*8;
;   const bf16*vsrc=Vh+(long)(16*(wid&3)+(lane>>2))*KP+(wid>>2)*32+(lane&3)*8;
;   const unsigned kdst=lds0+LDS_K+wid*1024, vdst=lds0+LDS_V+wid*1024;
;     ...
;   const int vb0=(int)(lds0+LDS_V)+((lane>>4)&1)*32+(lane&3)*8+(4*hi+((lane&15)>>2))*64;
;   const int s1=(s0==(NSLOT-1)*SLOTB)?0:s0+SLOTB, s2=(s1==(NSLOT-1)*SLOTB)?0:s1+SLOTB;
;   const char*Kbase=shm+LDS_K+s0; bf16x8 kf[8];
;   const lds_cptr shm3=(lds_cptr)shm; const lds_cptr kp0=shm3+LDS_K+hi*1024+r32*16; const lds_cptr vp0=shm3+LDS_V+((lane>>4)&1)*32+(lane&3)*8+(4*hi+((lane&15)>>2))*64;
.LBB0_925:
	s_cmpk_gt_i32 s92, 0xff
	s_waitcnt vmcnt(0) lgkmcnt(0)
	s_barrier
	s_cbranch_scc1 .LBB0_1021
	v_mov_b32_e32 v3, 0x1a0000
	global_load_dword v192, v3, s[66:67]
	v_and_b32_e32 v0, 63, v252
	v_and_b32_e32 v1, 31, v252
	v_bfe_u32 v2, v252, 5, 1
	v_lshrrev_b32_e32 v3, 6, v252
	s_nop 0
	v_readfirstlane_b32 s4, v3
	s_and_b32 s5, s4, 3
	s_lshr_b32 s6, s4, 2
	s_mov_b32 s48, 0x41000000
	v_lshlrev_b32_e32 v208, 10, v2
	v_lshl_add_u32 v208, v1, 4, v208
	s_lshl_b32 s34, s6, 9
	v_add_u32_e32 v208, s34, v208
	v_bfe_u32 v193, v0, 4, 1
	v_lshlrev_b32_e32 v209, 5, v193
	v_and_b32_e32 v193, 3, v0
	v_lshl_add_u32 v209, v193, 3, v209
	v_bfe_u32 v193, v0, 2, 2
	v_lshl_add_u32 v193, v2, 2, v193
	v_lshl_add_u32 v209, v193, 6, v209
	s_lshl_b32 s34, s6, 11
	v_add_u32_e32 v209, s34, v209
	s_lshl_b32 s34, s4, 10
	s_add_i32 s34, s34, 0x18000
	v_mov_b32_e32 v210, s34
	v_lshlrev_b32_e32 v215, 2, v1
	v_lshlrev_b32_e32 v216, 4, v2
	s_lshl_b32 s34, s4, 4
	v_lshlrev_b32_e32 v211, 10, v0
	v_add_u32_e32 v211, s34, v211
	v_lshrrev_b32_e32 v193, 2, v0
	v_lshlrev_b32_e32 v212, 10, v193
	v_and_b32_e32 v193, 3, v0
	v_lshl_add_u32 v212, v193, 4, v212
	s_lshl_b32 s34, s5, 14
	s_lshl_b32 s35, s6, 6
	s_add_i32 s34, s34, s35
	v_add_u32_e32 v212, s34, v212
	v_add_u32_e32 v213, 0x80, v212
	v_lshlrev_b32_e32 v214, 10, v1
	v_lshl_add_u32 v214, v2, 4, v214
	v_lshlrev_b32_e32 v217, 4, v0
	v_lshlrev_b32_e32 v218, 4, v0
	v_add_u32_e32 v218, 0x1000, v218
	v_lshlrev_b32_e32 v219, 4, v0
	v_add_u32_e32 v219, 0x2000, v219
	v_lshlrev_b32_e32 v220, 4, v0
	v_add_u32_e32 v220, 0x3000, v220
	s_lshl_b32 s34, s5, 14
	v_lshlrev_b32_e32 v222, 4, v0
	v_add_u32_e32 v222, s34, v222
	s_lshl_b32 s34, s92, 2
	s_add_i32 s34, s34, s5
	s_lshl_b32 s34, s34, 14
	s_add_u32 s52, s66, s34
	s_addc_u32 s53, s67, 0
	s_add_u32 s52, s52, 0x6f00000
	s_addc_u32 s53, s53, 0
	s_waitcnt vmcnt(0)
	v_readfirstlane_b32 s7, v192
	s_mov_b32 s8, s92

;   #define DMA_K(t,slot) glds16(ksrc+(long)(t)*KVBLK*KP,(unsigned)__builtin_amdgcn_readfirstlane(kdst+(slot)))
;   #define DMA_V(t,slot) glds16(vsrc+(long)(t)*KVBLK*KP,(unsigned)__builtin_amdgcn_readfirstlane(vdst+(slot)))
; template<int THRL,bool PART> __device__ __forceinline__ int attn_unit(const bf16*Qb,const bf16*__restrict__ Kh,const bf16*__restrict__ Vh,bf16*Ob,const int NT,const int vlim_in,char*shm,const int s0,const bool primed,const bf16*nKh,const bf16*nVh,bf16*fuseM,const float lam){
;     ...
;   const bf16*Qw=Qb+(long)(wid*QBLK)*KP;
;   const unsigned lds0=(unsigned)(uintptr_t)shm;
;   float*wsf=(float*)(shm+LDS_WS)+wid*64;
;   const bf16*ksrc=Kh+(long)lane*KP+wid*8;
;   const bf16*vsrc=Vh+(long)(16*(wid&3)+(lane>>2))*KP+(wid>>2)*32+(lane&3)*8;
;   const unsigned kdst=lds0+LDS_K+wid*1024, vdst=lds0+LDS_V+wid*1024;
;     ...
;   const int vb0=(int)(lds0+LDS_V)+((lane>>4)&1)*32+(lane&3)*8+(4*hi+((lane&15)>>2))*64;
;   const int s1=(s0==(NSLOT-1)*SLOTB)?0:s0+SLOTB, s2=(s1==(NSLOT-1)*SLOTB)?0:s1+SLOTB;
;   const char*Kbase=shm+LDS_K+s0; bf16x8 kf[8];
;   const lds_cptr shm3=(lds_cptr)shm; const lds_cptr kp0=shm3+LDS_K+hi*1024+r32*16; const lds_cptr vp0=shm3+LDS_V+((lane>>4)&1)*32+(lane&3)*8+(4*hi+((lane&15)>>2))*64;
;   if(!primed){DMA_K(0,s0);DMA_V(0,s0);DMA_K(1,s1);}
;   bf16x8 qr[4];
;   #pragma unroll
;   for(int d0=0;d0<4;++d0)qr[d0]=*reinterpret_cast<const bf16x8*>(&Qw[(long)r32*KP+d0*16+hi*8]);
;   float zz_=0.f;asm volatile("":"+v"(zz_));
;   float mhat=zz_,l_reg=zz_;f32x16 o[2];
;   _Pragma("unroll") for(int r=0;r<16;++r){o[0][r]=zz_;o[1][r]=zz_;}
;   f32x16 negm;
;   _Pragma("unroll") for(int r=0;r<16;++r)negm[r]=zz_;
;   asm volatile("":"+v"(negm));
.Lat_j:
	s_lshl_b32 s34, s10, 1
	s_add_i32 s34, s34, s14
	s_add_u32 s18, s66, 0xf300000
	s_addc_u32 s19, s67, 0
	s_lshl_b32 s36, s9, 22
	s_add_u32 s18, s18, s36
	s_addc_u32 s19, s19, 0
	s_lshl_b32 s36, s34, 7
	s_add_u32 s18, s18, s36
	s_addc_u32 s19, s19, 0
	s_add_u32 s20, s66, 0x12200000
	s_addc_u32 s21, s67, 0
	s_lshl_b32 s36, s9, 22
	s_add_u32 s20, s20, s36
	s_addc_u32 s21, s21, 0
	s_lshl_b32 s36, s10, 8
	s_add_u32 s20, s20, s36
	s_addc_u32 s21, s21, 0
	s_add_u32 s22, s66, 0xd100000
	s_addc_u32 s23, s67, 0
	s_lshl_b32 s36, s9, 22
	s_add_u32 s22, s22, s36
	s_addc_u32 s23, s23, 0
	s_lshl_b32 s36, s13, 17
	s_add_u32 s22, s22, s36
	s_addc_u32 s23, s23, 0
	s_lshl_b32 s36, s5, 15
	s_add_u32 s22, s22, s36
	s_addc_u32 s23, s23, 0
	s_lshl_b32 s36, s34, 7
	s_add_u32 s22, s22, s36
	s_addc_u32 s23, s23, 0
	s_mov_b32 s17, 0
	s_mov_b32 s24, 0
	global_load_dwordx4 v[4:7], v214, s[22:23]
	global_load_dwordx4 v[8:11], v214, s[22:23] offset:32
	global_load_dwordx4 v[12:15], v214, s[22:23] offset:64
	global_load_dwordx4 v[16:19], v214, s[22:23] offset:96
	s_mov_b32 s27, 0x0
	s_lshl_b32 s37, s4, 10
	s_add_i32 m0, s37, s27
	s_nop 0
	global_load_lds_dwordx4 v211, s[18:19]
	s_add_u32 s18, s18, 0x10000
	s_addc_u32 s19, s19, 0
	s_mov_b32 s27, 0x2000
	s_lshl_b32 s37, s4, 10
	s_add_i32 m0, s37, s27
	s_nop 0
	global_load_lds_dwordx4 v211, s[18:19]
	s_add_u32 s18, s18, 0x10000
	s_addc_u32 s19, s19, 0
	s_cmp_gt_u32 s15, 2
	s_cbranch_scc0 .Lat_kdone1
	s_mov_b32 s27, 0x4000
	s_lshl_b32 s37, s4, 10
	s_add_i32 m0, s37, s27
	s_nop 0
	global_load_lds_dwordx4 v211, s[18:19]
	s_add_u32 s18, s18, 0x10000
	s_addc_u32 s19, s19, 0
	s_cmp_gt_u32 s15, 3
	s_cbranch_scc0 .Lat_kdone1
	s_mov_b32 s27, 0x6000
	s_lshl_b32 s37, s4, 10
	s_add_i32 m0, s37, s27
	s_nop 0
	global_load_lds_dwordx4 v211, s[18:19]
	s_add_u32 s18, s18, 0x10000
	s_addc_u32 s19, s19, 0
.Lat_kdone1:
	s_mov_b32 s29, 0x8000
	s_lshl_b32 s37, s4, 10
	s_add_i32 m0, s37, s29
	s_nop 0
	global_load_lds_dwordx4 v212, s[20:21]
	s_add_i32 m0, m0, 0x2000
	s_nop 0
	global_load_lds_dwordx4 v213, s[20:21]
	s_add_u32 s20, s20, 0x10000
	s_addc_u32 s21, s21, 0
	s_mov_b32 s29, 0xc000
	s_lshl_b32 s37, s4, 10
	s_add_i32 m0, s37, s29
	s_nop 0
	global_load_lds_dwordx4 v212, s[20:21]
	s_add_i32 m0, m0, 0x2000
	s_nop 0
	global_load_lds_dwordx4 v213, s[20:21]
	s_add_u32 s20, s20, 0x10000
	s_addc_u32 s21, s21, 0
	v_mov_b32_e32 v124, 0
	v_mov_b32_e32 v125, 0
	v_mov_b32_e32 v126, 0
	v_mov_b32_e32 v127, 0
	v_mov_b32_e32 v128, 0
	v_mov_b32_e32 v129, 0
	v_mov_b32_e32 v130, 0
	v_mov_b32_e32 v131, 0
	v_mov_b32_e32 v132, 0
	v_mov_b32_e32 v133, 0
	v_mov_b32_e32 v134, 0
	v_mov_b32_e32 v135, 0
	v_mov_b32_e32 v136, 0
	v_mov_b32_e32 v137, 0
	v_mov_b32_e32 v138, 0
	v_mov_b32_e32 v139, 0
	v_mov_b32_e32 v140, 0
	v_mov_b32_e32 v141, 0
	v_mov_b32_e32 v142, 0
	v_mov_b32_e32 v143, 0
	v_mov_b32_e32 v144, 0
	v_mov_b32_e32 v145, 0
	v_mov_b32_e32 v146, 0
	v_mov_b32_e32 v147, 0
	v_mov_b32_e32 v148, 0
	v_mov_b32_e32 v149, 0
	v_mov_b32_e32 v150, 0
	v_mov_b32_e32 v151, 0
	v_mov_b32_e32 v152, 0
	v_mov_b32_e32 v153, 0
	v_mov_b32_e32 v154, 0
	v_mov_b32_e32 v155, 0
	v_mov_b32_e32 v156, 0
	v_mov_b32_e32 v157, 0
	v_mov_b32_e32 v158, 0
	v_mov_b32_e32 v159, 0
	v_mov_b32_e32 v160, 0
	v_mov_b32_e32 v161, 0
	v_mov_b32_e32 v162, 0
	v_mov_b32_e32 v163, 0
	v_mov_b32_e32 v164, 0
	v_mov_b32_e32 v165, 0
	v_mov_b32_e32 v166, 0
	v_mov_b32_e32 v167, 0
	v_mov_b32_e32 v168, 0
	v_mov_b32_e32 v169, 0
	v_mov_b32_e32 v170, 0
	v_mov_b32_e32 v171, 0
	v_mov_b32_e32 v172, 0
	v_mov_b32_e32 v173, 0
	v_mov_b32_e32 v174, 0
	v_mov_b32_e32 v175, 0
	v_mov_b32_e32 v176, 0
	v_mov_b32_e32 v177, 0
	v_mov_b32_e32 v178, 0
	v_mov_b32_e32 v179, 0
	v_mov_b32_e32 v180, 0
	v_mov_b32_e32 v181, 0
	v_mov_b32_e32 v182, 0
	v_mov_b32_e32 v183, 0
	v_mov_b32_e32 v184, 0
	v_mov_b32_e32 v185, 0
	v_mov_b32_e32 v186, 0
	v_mov_b32_e32 v187, 0
	v_mov_b32_e32 v68, 0
	v_mov_b32_e32 v69, 0
	v_mov_b32_e32 v70, 0
	v_mov_b32_e32 v71, 0
	v_mov_b32_e32 v72, 0
	v_mov_b32_e32 v73, 0
	v_mov_b32_e32 v74, 0
	v_mov_b32_e32 v75, 0
	v_mov_b32_e32 v76, 0
	v_mov_b32_e32 v77, 0
	v_mov_b32_e32 v78, 0
	v_mov_b32_e32 v79, 0
	v_mov_b32_e32 v80, 0
	v_mov_b32_e32 v81, 0
	v_mov_b32_e32 v82, 0
	v_mov_b32_e32 v83, 0
	v_mov_b32_e32 v188, 0
	v_mov_b32_e32 v189, 0
	s_waitcnt vmcnt(0)
	s_barrier
	v_mov_b32_e32 v192, v208
	ds_read_b128 v[20:23], v192 offset:0
	ds_read_b128 v[24:27], v192 offset:2048
	ds_read_b128 v[28:31], v192 offset:4096
	ds_read_b128 v[32:35], v192 offset:6144
.Lat_t2:
	s_add_i32 s26, s24, 1
	s_and_b32 s26, s26, 3
	s_lshl_b32 s26, s26, 13
	s_lshl_b32 s27, s24, 13
	s_add_i32 s28, s24, 3
	s_and_b32 s28, s28, 3
	s_lshl_b32 s28, s28, 14
	s_add_i32 s28, s28, 0x8000
	s_add_i32 s29, s24, 2
	s_and_b32 s29, s29, 3
	s_lshl_b32 s29, s29, 14
	s_add_i32 s29, s29, 0x8000
	s_cmp_lt_u32 s17, s16
	s_cbranch_scc0 .Lat_last5
	s_cmp_eq_u32 s17, 0
	s_cbranch_scc1 .Lat_first4
	v_add_u32_e32 v193, s28, v209
	ds_read_b64_tr_b16 v[92:93], v193 offset:0
	ds_read_b64_tr_b16 v[94:95], v193 offset:512
	ds_read_b64_tr_b16 v[100:101], v193 offset:4096
	ds_read_b64_tr_b16 v[102:103], v193 offset:4608
	v_mfma_f32_32x32x16_bf16 v[36:51], v[20:23], v[4:7], v[68:83]
	v_add_f32_e32 v221, v52, v53
	v_add_f32_e32 v221, v221, v54
	v_add_f32_e32 v221, v221, v55
	v_add_f32_e32 v221, v221, v56
	v_add_f32_e32 v221, v221, v57
	v_cvt_pk_bf16_f32 v84, v52, v53
	v_cvt_pk_bf16_f32 v85, v54, v55
	ds_read_b64_tr_b16 v[108:109], v193 offset:8192
	ds_read_b64_tr_b16 v[110:111], v193 offset:8704
	ds_read_b64_tr_b16 v[116:117], v193 offset:12288
	ds_read_b64_tr_b16 v[118:119], v193 offset:12800
	v_mfma_f32_32x32x16_bf16 v[36:51], v[24:27], v[8:11], v[36:51]
	v_add_f32_e32 v221, v221, v58
	v_add_f32_e32 v221, v221, v59
	v_add_f32_e32 v221, v221, v60
	v_add_f32_e32 v221, v221, v61
	v_cvt_pk_bf16_f32 v86, v56, v57
	v_cvt_pk_bf16_f32 v87, v58, v59
	ds_read_b64_tr_b16 v[96:97], v193 offset:1024
	ds_read_b64_tr_b16 v[98:99], v193 offset:1536
	ds_read_b64_tr_b16 v[104:105], v193 offset:5120
	ds_read_b64_tr_b16 v[106:107], v193 offset:5632
	v_mfma_f32_32x32x16_bf16 v[36:51], v[28:31], v[12:15], v[36:51]
	v_add_f32_e32 v221, v221, v62
	v_add_f32_e32 v221, v221, v63
	v_add_f32_e32 v221, v221, v64
	v_add_f32_e32 v221, v221, v65
	v_cvt_pk_bf16_f32 v88, v60, v61
	v_cvt_pk_bf16_f32 v89, v62, v63
	ds_read_b64_tr_b16 v[112:113], v193 offset:9216
	ds_read_b64_tr_b16 v[114:115], v193 offset:9728
	ds_read_b64_tr_b16 v[120:121], v193 offset:13312
	ds_read_b64_tr_b16 v[122:123], v193 offset:13824
	v_mfma_f32_32x32x16_bf16 v[36:51], v[32:35], v[16:19], v[36:51]
	v_add_f32_e32 v221, v221, v66
	v_add_f32_e32 v221, v221, v67
	v_cvt_pk_bf16_f32 v90, v64, v65
	v_cvt_pk_bf16_f32 v91, v66, v67
	v_add_f32_e32 v189, v189, v221
	s_nop 6
	v_max3_f32 v194, v36, v37, v38
	v_max3_f32 v195, v39, v40, v41
	v_max3_f32 v194, v194, v42, v43
	v_max3_f32 v195, v195, v44, v45
	v_max3_f32 v194, v194, v46, v47
	v_max3_f32 v195, v195, v48, v49
	v_max3_f32 v194, v194, v50, v51
	v_max_f32_e32 v190, v194, v195
	v_mov_b32_e32 v194, v190
	s_nop 1
	v_permlane32_swap_b32_e32 v190, v194
	v_max_f32_e32 v190, v190, v194
	s_mov_b32 s54, 0
	v_cmp_lt_f32_e32 vcc, s48, v190
	s_nop 0
	s_cmp_lg_u64 vcc, 0
	s_cbranch_scc0 .Lat_nores7
	v_max_f32_e32 v190, 0, v190
	v_add_f32_e32 v188, v188, v190
	v_sub_f32_e32 v36, v36, v190
	v_sub_f32_e32 v37, v37, v190
	v_sub_f32_e32 v38, v38, v190
	v_sub_f32_e32 v39, v39, v190
	v_sub_f32_e32 v40, v40, v190
	v_sub_f32_e32 v41, v41, v190
	v_sub_f32_e32 v42, v42, v190
	v_sub_f32_e32 v43, v43, v190
	v_sub_f32_e32 v44, v44, v190
	v_sub_f32_e32 v45, v45, v190
	v_sub_f32_e32 v46, v46, v190
	v_sub_f32_e32 v47, v47, v190
	v_sub_f32_e32 v48, v48, v190
	v_sub_f32_e32 v49, v49, v190
	v_sub_f32_e32 v50, v50, v190
	v_sub_f32_e32 v51, v51, v190
	v_xor_b32_e32 v68, 0x80000000, v188
	v_xor_b32_e32 v69, 0x80000000, v188
	v_xor_b32_e32 v70, 0x80000000, v188
	v_xor_b32_e32 v71, 0x80000000, v188
	v_xor_b32_e32 v72, 0x80000000, v188
	v_xor_b32_e32 v73, 0x80000000, v188
	v_xor_b32_e32 v74, 0x80000000, v188
	v_xor_b32_e32 v75, 0x80000000, v188
	v_xor_b32_e32 v76, 0x80000000, v188
	v_xor_b32_e32 v77, 0x80000000, v188
	v_xor_b32_e32 v78, 0x80000000, v188
	v_xor_b32_e32 v79, 0x80000000, v188
	v_xor_b32_e32 v80, 0x80000000, v188
	v_xor_b32_e32 v81, 0x80000000, v188
	v_xor_b32_e32 v82, 0x80000000, v188
	v_xor_b32_e32 v83, 0x80000000, v188
	v_exp_f32_e64 v191, -v190
	s_mov_b32 s54, 1
	v_add_u32_e32 v197, v210, v215
	v_mul_f32_e32 v189, v189, v191
	ds_write_b32 v197, v191 offset:0
.Lat_nores7:
	v_add_u32_e32 v192, s26, v208
	s_waitcnt lgkmcnt(0)
	v_mfma_f32_32x32x16_bf16 v[124:139], v[84:87], v[92:95], v[124:139]
	v_exp_f32_e32 v36, v36
	v_exp_f32_e32 v37, v37
	v_mfma_f32_32x32x16_bf16 v[140:155], v[84:87], v[100:103], v[140:155]
	v_exp_f32_e32 v38, v38
	v_exp_f32_e32 v39, v39
	s_add_i32 s34, s17, 1
	s_cmp_lt_u32 s34, s16
	s_cbranch_scc0 .Lat_nokf8
	v_mfma_f32_32x32x16_bf16 v[156:171], v[84:87], v[108:111], v[156:171]
	v_exp_f32_e32 v40, v40
	v_exp_f32_e32 v41, v41
	ds_read_b128 v[20:23], v192 offset:0
	v_mfma_f32_32x32x16_bf16 v[172:187], v[84:87], v[116:119], v[172:187]
	v_exp_f32_e32 v42, v42
	v_exp_f32_e32 v43, v43
	ds_read_b128 v[24:27], v192 offset:2048
	v_mfma_f32_32x32x16_bf16 v[124:139], v[88:91], v[96:99], v[124:139]
	v_exp_f32_e32 v44, v44
	v_exp_f32_e32 v45, v45
	ds_read_b128 v[28:31], v192 offset:4096
	v_mfma_f32_32x32x16_bf16 v[140:155], v[88:91], v[104:107], v[140:155]
	v_exp_f32_e32 v46, v46
	v_exp_f32_e32 v47, v47
	ds_read_b128 v[32:35], v192 offset:6144
	v_mfma_f32_32x32x16_bf16 v[156:171], v[88:91], v[112:115], v[156:171]
	v_exp_f32_e32 v48, v48
	v_exp_f32_e32 v49, v49
	v_mfma_f32_32x32x16_bf16 v[172:187], v[88:91], v[120:123], v[172:187]
	v_exp_f32_e32 v50, v50
	v_exp_f32_e32 v51, v51
	s_branch .Lat_end6
.Lat_nokf8:
	v_mfma_f32_32x32x16_bf16 v[156:171], v[84:87], v[108:111], v[156:171]
	v_exp_f32_e32 v40, v40
	v_exp_f32_e32 v41, v41
	v_mfma_f32_32x32x16_bf16 v[172:187], v[84:87], v[116:119], v[172:187]
	v_exp_f32_e32 v42, v42
	v_exp_f32_e32 v43, v43
	v_mfma_f32_32x32x16_bf16 v[124:139], v[88:91], v[96:99], v[124:139]
	v_exp_f32_e32 v44, v44
	v_exp_f32_e32 v45, v45
	v_mfma_f32_32x32x16_bf16 v[140:155], v[88:91], v[104:107], v[140:155]
	v_exp_f32_e32 v46, v46
	v_exp_f32_e32 v47, v47
	v_mfma_f32_32x32x16_bf16 v[156:171], v[88:91], v[112:115], v[156:171]
	v_exp_f32_e32 v48, v48
	v_exp_f32_e32 v49, v49
	v_mfma_f32_32x32x16_bf16 v[172:187], v[88:91], v[120:123], v[172:187]
	v_exp_f32_e32 v50, v50
	v_exp_f32_e32 v51, v51
	s_branch .Lat_end6
; #define SBAR() __builtin_amdgcn_sched_barrier(0)
;   #define CMASK(P0,P1,t) do{int jb_=(t)-(NT-4); if(jb_>=0)cmask(P0,P1,jb_,vlim);}while(0)
;   #define START(P0,P1) do{ const float rm=rowmax(P0,P1); resc=false; \
;     { const float dl=rm; mhat=fadd_s(mhat,dl); \
;       _Pragma("unroll") for(int r=0;r<16;++r){P0[r]=fsub_s(P0[r],dl);P1[r]=fsub_s(P1[r],dl);} \
;       _Pragma("unroll") for(int r=0;r<16;++r)negm[r]=-mhat; asm volatile("":"+v"(negm)); } \
;     _Pragma("unroll") for(int r=0;r<16;++r)P0[r]=__builtin_amdgcn_exp2f(P0[r]); }while(0)
;   #define RESC() do{ if(resc){ asm volatile("s_waitcnt lgkmcnt(0)":::"memory"); \
;       _Pragma("unroll") for(int d_=0;d_<2;++d_) _Pragma("unroll") for(int r=0;r<16;++r)o[d_][r]*=wsf[crow(r,hi)]; } }while(0)
;   #define PKW(P,B) cvtpk_s(P[B],P[B+1])
;   #define CMASK(P0,P1,t) do{}while(0)
;   #define CMASK(P0,P1,t) do{int jb_=(t)-(NT-4); if(jb_>=0)cmask(P0,P1,jb_,vlim);}while(0)
; template<int THRL,bool PART> __device__ __forceinline__ int attn_unit(const bf16*Qb,const bf16*__restrict__ Kh,const bf16*__restrict__ Vh,bf16*Ob,const int NT,const int vlim_in,char*shm,const int s0,const bool primed,const bf16*nKh,const bf16*nVh,bf16*fuseM,const float lam){
;     ...
;   if(act){
;   qkt(pA0,pA1,Kbase,qr,negm,r32,hi);asm volatile("s_nop 15\n\ts_nop 7":"+v"(pA0),"+v"(pA1));CMASK(pA0,pA1,0);
;   START(pA0,pA1);
;   _Pragma("unroll") for(int r=0;r<16;++r)pA1[r]=__builtin_amdgcn_exp2f(pA1[r]);
;   }
;     ...
;   STEP(pB0,pB1,pA0,pA1,NT-1,false,false,false); RESC();
;   if(act){ float sacc=pB0[0]+pB0[1]; _Pragma("unroll") for(int r=2;r<16;++r)sacc+=pB0[r]; _Pragma("unroll") for(int r=0;r<16;++r)sacc+=pB1[r]; l_reg+=sacc;
;     pw0=(u32x4){PKW(pB0,0),PKW(pB0,2),PKW(pB0,4),PKW(pB0,6)};pw1=(u32x4){PKW(pB0,8),PKW(pB0,10),PKW(pB0,12),PKW(pB0,14)};pw2=(u32x4){PKW(pB1,0),PKW(pB1,2),PKW(pB1,4),PKW(pB1,6)};pw3=(u32x4){PKW(pB1,8),PKW(pB1,10),PKW(pB1,12),PKW(pB1,14)};
;     SBAR(); pv(o,vb0+sl_cur,PAF(0),PAF(1),PAF(2),PAF(3)); }
.Lat_first4:
	s_waitcnt lgkmcnt(0)
	v_mfma_f32_32x32x16_bf16 v[36:51], v[20:23], v[4:7], v[68:83]
	v_mfma_f32_32x32x16_bf16 v[36:51], v[24:27], v[8:11], v[36:51]
	v_mfma_f32_32x32x16_bf16 v[36:51], v[28:31], v[12:15], v[36:51]
	v_mfma_f32_32x32x16_bf16 v[36:51], v[32:35], v[16:19], v[36:51]
	s_nop 7
	s_nop 4
	v_max3_f32 v194, v36, v37, v38
	v_max3_f32 v195, v39, v40, v41
	v_max3_f32 v194, v194, v42, v43
	v_max3_f32 v195, v195, v44, v45
	v_max3_f32 v194, v194, v46, v47
	v_max3_f32 v195, v195, v48, v49
	v_max3_f32 v194, v194, v50, v51
	v_max_f32_e32 v190, v194, v195
	v_mov_b32_e32 v194, v190
	s_nop 1
	v_permlane32_swap_b32_e32 v190, v194
	v_max_f32_e32 v190, v190, v194
	s_mov_b32 s54, 0
	v_mov_b32_e32 v188, v190
	v_sub_f32_e32 v36, v36, v190
	v_sub_f32_e32 v37, v37, v190
	v_sub_f32_e32 v38, v38, v190
	v_sub_f32_e32 v39, v39, v190
	v_sub_f32_e32 v40, v40, v190
	v_sub_f32_e32 v41, v41, v190
	v_sub_f32_e32 v42, v42, v190
	v_sub_f32_e32 v43, v43, v190
	v_sub_f32_e32 v44, v44, v190
	v_sub_f32_e32 v45, v45, v190
	v_sub_f32_e32 v46, v46, v190
	v_sub_f32_e32 v47, v47, v190
	v_sub_f32_e32 v48, v48, v190
	v_sub_f32_e32 v49, v49, v190
	v_sub_f32_e32 v50, v50, v190
	v_sub_f32_e32 v51, v51, v190
	v_xor_b32_e32 v68, 0x80000000, v188
	v_xor_b32_e32 v69, 0x80000000, v188
	v_xor_b32_e32 v70, 0x80000000, v188
	v_xor_b32_e32 v71, 0x80000000, v188
	v_xor_b32_e32 v72, 0x80000000, v188
	v_xor_b32_e32 v73, 0x80000000, v188
	v_xor_b32_e32 v74, 0x80000000, v188
	v_xor_b32_e32 v75, 0x80000000, v188
	v_xor_b32_e32 v76, 0x80000000, v188
	v_xor_b32_e32 v77, 0x80000000, v188
	v_xor_b32_e32 v78, 0x80000000, v188
	v_xor_b32_e32 v79, 0x80000000, v188
	v_xor_b32_e32 v80, 0x80000000, v188
	v_xor_b32_e32 v81, 0x80000000, v188
	v_xor_b32_e32 v82, 0x80000000, v188
	v_xor_b32_e32 v83, 0x80000000, v188
	s_cmp_gt_u32 s16, 1
	s_cbranch_scc0 .Lat_nokf9
	v_add_u32_e32 v192, s26, v208
	ds_read_b128 v[20:23], v192 offset:0
	ds_read_b128 v[24:27], v192 offset:2048
	ds_read_b128 v[28:31], v192 offset:4096
	ds_read_b128 v[32:35], v192 offset:6144
.Lat_nokf9:
	v_exp_f32_e32 v36, v36
	v_exp_f32_e32 v37, v37
	v_exp_f32_e32 v38, v38
	v_exp_f32_e32 v39, v39
	v_exp_f32_e32 v40, v40
	v_exp_f32_e32 v41, v41
	v_exp_f32_e32 v42, v42
	v_exp_f32_e32 v43, v43
	v_exp_f32_e32 v44, v44
	v_exp_f32_e32 v45, v45
	v_exp_f32_e32 v46, v46
	v_exp_f32_e32 v47, v47
	v_exp_f32_e32 v48, v48
	v_exp_f32_e32 v49, v49
	v_exp_f32_e32 v50, v50
	v_exp_f32_e32 v51, v51
	s_branch .Lat_end6
.Lat_last5:
	s_mov_b32 s54, 0
	s_cmp_eq_u32 s17, s16
	s_cbranch_scc0 .Lat_end6
	v_add_u32_e32 v193, s28, v209
	ds_read_b64_tr_b16 v[92:93], v193 offset:0
	ds_read_b64_tr_b16 v[94:95], v193 offset:512
	ds_read_b64_tr_b16 v[100:101], v193 offset:4096
	ds_read_b64_tr_b16 v[102:103], v193 offset:4608
	v_add_f32_e32 v221, v52, v53
	v_add_f32_e32 v221, v221, v54
	v_add_f32_e32 v221, v221, v55
	v_add_f32_e32 v221, v221, v56
	v_add_f32_e32 v221, v221, v57
	v_cvt_pk_bf16_f32 v84, v52, v53
	v_cvt_pk_bf16_f32 v85, v54, v55
	ds_read_b64_tr_b16 v[108:109], v193 offset:8192
	ds_read_b64_tr_b16 v[110:111], v193 offset:8704
	ds_read_b64_tr_b16 v[116:117], v193 offset:12288
	ds_read_b64_tr_b16 v[118:119], v193 offset:12800
	v_add_f32_e32 v221, v221, v58
	v_add_f32_e32 v221, v221, v59
	v_add_f32_e32 v221, v221, v60
	v_add_f32_e32 v221, v221, v61
	v_cvt_pk_bf16_f32 v86, v56, v57
	v_cvt_pk_bf16_f32 v87, v58, v59
	ds_read_b64_tr_b16 v[96:97], v193 offset:1024
	ds_read_b64_tr_b16 v[98:99], v193 offset:1536
	ds_read_b64_tr_b16 v[104:105], v193 offset:5120
	ds_read_b64_tr_b16 v[106:107], v193 offset:5632
	v_add_f32_e32 v221, v221, v62
	v_add_f32_e32 v221, v221, v63
	v_add_f32_e32 v221, v221, v64
	v_add_f32_e32 v221, v221, v65
	v_cvt_pk_bf16_f32 v88, v60, v61
	v_cvt_pk_bf16_f32 v89, v62, v63
	ds_read_b64_tr_b16 v[112:113], v193 offset:9216
	ds_read_b64_tr_b16 v[114:115], v193 offset:9728
	ds_read_b64_tr_b16 v[120:121], v193 offset:13312
	ds_read_b64_tr_b16 v[122:123], v193 offset:13824
	v_add_f32_e32 v221, v221, v66
	v_add_f32_e32 v221, v221, v67
	v_cvt_pk_bf16_f32 v90, v64, v65
	v_cvt_pk_bf16_f32 v91, v66, v67
	v_add_f32_e32 v189, v189, v221
	s_waitcnt lgkmcnt(0)
	v_mfma_f32_32x32x16_bf16 v[124:139], v[84:87], v[92:95], v[124:139]
	v_mfma_f32_32x32x16_bf16 v[140:155], v[84:87], v[100:103], v[140:155]
	v_mfma_f32_32x32x16_bf16 v[156:171], v[84:87], v[108:111], v[156:171]
	v_mfma_f32_32x32x16_bf16 v[172:187], v[84:87], v[116:119], v[172:187]
	v_mfma_f32_32x32x16_bf16 v[124:139], v[88:91], v[96:99], v[124:139]
	v_mfma_f32_32x32x16_bf16 v[140:155], v[88:91], v[104:107], v[140:155]
	v_mfma_f32_32x32x16_bf16 v[156:171], v[88:91], v[112:115], v[156:171]
	v_mfma_f32_32x32x16_bf16 v[172:187], v[88:91], v[120:123], v[172:187]
.Lat_end6:
	s_cmp_eq_u32 s54, 0
	s_cbranch_scc1 .Lat_nor10
	v_add_u32_e32 v197, v210, v216
	ds_read_b128 v[92:95], v197 offset:0
	ds_read_b128 v[96:99], v197 offset:32
	ds_read_b128 v[100:103], v197 offset:64
	ds_read_b128 v[104:107], v197 offset:96
	s_nop 7
	s_nop 3
	s_waitcnt lgkmcnt(0)
	v_mul_f32_e32 v124, v124, v92
	v_mul_f32_e32 v125, v125, v93
	v_mul_f32_e32 v126, v126, v94
	v_mul_f32_e32 v127, v127, v95
	v_mul_f32_e32 v128, v128, v96
	v_mul_f32_e32 v129, v129, v97
	v_mul_f32_e32 v130, v130, v98
	v_mul_f32_e32 v131, v131, v99
	v_mul_f32_e32 v132, v132, v100
	v_mul_f32_e32 v133, v133, v101
	v_mul_f32_e32 v134, v134, v102
	v_mul_f32_e32 v135, v135, v103
	v_mul_f32_e32 v136, v136, v104
	v_mul_f32_e32 v137, v137, v105
	v_mul_f32_e32 v138, v138, v106
	v_mul_f32_e32 v139, v139, v107
	v_mul_f32_e32 v140, v140, v92
	v_mul_f32_e32 v141, v141, v93
	v_mul_f32_e32 v142, v142, v94
	v_mul_f32_e32 v143, v143, v95
	v_mul_f32_e32 v144, v144, v96
	v_mul_f32_e32 v145, v145, v97
	v_mul_f32_e32 v146, v146, v98
	v_mul_f32_e32 v147, v147, v99
	v_mul_f32_e32 v148, v148, v100
	v_mul_f32_e32 v149, v149, v101
	v_mul_f32_e32 v150, v150, v102
	v_mul_f32_e32 v151, v151, v103
	v_mul_f32_e32 v152, v152, v104
	v_mul_f32_e32 v153, v153, v105
	v_mul_f32_e32 v154, v154, v106
	v_mul_f32_e32 v155, v155, v107
	v_mul_f32_e32 v156, v156, v92
	v_mul_f32_e32 v157, v157, v93
	v_mul_f32_e32 v158, v158, v94
	v_mul_f32_e32 v159, v159, v95
	v_mul_f32_e32 v160, v160, v96
	v_mul_f32_e32 v161, v161, v97
	v_mul_f32_e32 v162, v162, v98
	v_mul_f32_e32 v163, v163, v99
	v_mul_f32_e32 v164, v164, v100
	v_mul_f32_e32 v165, v165, v101
	v_mul_f32_e32 v166, v166, v102
	v_mul_f32_e32 v167, v167, v103
	v_mul_f32_e32 v168, v168, v104
	v_mul_f32_e32 v169, v169, v105
	v_mul_f32_e32 v170, v170, v106
	v_mul_f32_e32 v171, v171, v107
	v_mul_f32_e32 v172, v172, v92
	v_mul_f32_e32 v173, v173, v93
	v_mul_f32_e32 v174, v174, v94
	v_mul_f32_e32 v175, v175, v95
	v_mul_f32_e32 v176, v176, v96
	v_mul_f32_e32 v177, v177, v97
	v_mul_f32_e32 v178, v178, v98
	v_mul_f32_e32 v179, v179, v99
	v_mul_f32_e32 v180, v180, v100
	v_mul_f32_e32 v181, v181, v101
	v_mul_f32_e32 v182, v182, v102
	v_mul_f32_e32 v183, v183, v103
	v_mul_f32_e32 v184, v184, v104
	v_mul_f32_e32 v185, v185, v105
	v_mul_f32_e32 v186, v186, v106
	v_mul_f32_e32 v187, v187, v107
.Lat_nor10:
	s_add_i32 s34, s17, 4
	s_cmp_lt_u32 s34, s15
	s_cbranch_scc0 .Lat_dn11
	s_lshl_b32 s37, s4, 10
	s_add_i32 m0, s37, s27
	s_nop 0
	global_load_lds_dwordx4 v211, s[18:19]
	s_add_u32 s18, s18, 0x10000
	s_addc_u32 s19, s19, 0
	s_lshl_b32 s37, s4, 10
	s_add_i32 m0, s37, s29
	s_nop 0
	global_load_lds_dwordx4 v212, s[20:21]
	s_add_i32 m0, m0, 0x2000
	s_nop 0
	global_load_lds_dwordx4 v213, s[20:21]
	s_add_u32 s20, s20, 0x10000
	s_addc_u32 s21, s21, 0
	s_waitcnt vmcnt(6) lgkmcnt(0)
	s_branch .Lat_bar12
.Lat_dn11:
	s_add_i32 s34, s17, 2
	s_cmp_lt_u32 s34, s15
	s_cbranch_scc0 .Lat_dv13
	s_lshl_b32 s37, s4, 10
	s_add_i32 m0, s37, s29
	s_nop 0
	global_load_lds_dwordx4 v212, s[20:21]
	s_add_i32 m0, m0, 0x2000
	s_nop 0
	global_load_lds_dwordx4 v213, s[20:21]
	s_add_u32 s20, s20, 0x10000
	s_addc_u32 s21, s21, 0

; #define WAIT_BAR(N) asm volatile("s_waitcnt vmcnt(" #N ") lgkmcnt(0)\n\ts_barrier":::"memory")
;   #define RESC() do{ if(resc){ asm volatile("s_waitcnt lgkmcnt(0)":::"memory"); \
;       _Pragma("unroll") for(int d_=0;d_<2;++d_) _Pragma("unroll") for(int r=0;r<16;++r)o[d_][r]*=wsf[crow(r,hi)]; } }while(0)
;   #define ROT() do{sl_prev=sl_cur;sl_cur=sl_next;sl_next=(sl_next==(NSLOT-1)*SLOTB)?0:sl_next+SLOTB;}while(0)
; template<int THRL,bool PART> __device__ __forceinline__ int attn_unit(const bf16*Qb,const bf16*__restrict__ Kh,const bf16*__restrict__ Vh,bf16*Ob,const int NT,const int vlim_in,char*shm,const int s0,const bool primed,const bf16*nKh,const bf16*nVh,bf16*fuseM,const float lam){
;     ...
;   for(;t+5<NT;t+=2){
;     STEP(pB0,pB1,pA0,pA1,t,true,true,true);     WAIT_BAR(2); RESC(); ROT();
;     STEP(pA0,pA1,pB0,pB1,t+1,true,true,true);   WAIT_BAR(2); RESC(); ROT();
;   }
.Lat_bar12:
	s_barrier
	s_add_i32 s24, s24, 1
	s_and_b32 s24, s24, 3
	s_add_i32 s17, s17, 1
	s_cmp_le_u32 s17, s15
	s_cbranch_scc0 .Lat_tx3
	s_add_i32 s26, s24, 1
	s_and_b32 s26, s26, 3
	s_lshl_b32 s26, s26, 13
	s_lshl_b32 s27, s24, 13
	s_add_i32 s28, s24, 3
	s_and_b32 s28, s28, 3
	s_lshl_b32 s28, s28, 14
	s_add_i32 s28, s28, 0x8000
	s_add_i32 s29, s24, 2
	s_and_b32 s29, s29, 3
	s_lshl_b32 s29, s29, 14
	s_add_i32 s29, s29, 0x8000
	s_cmp_lt_u32 s17, s16
	s_cbranch_scc0 .Lat_last15
	v_add_u32_e32 v193, s28, v209
	ds_read_b64_tr_b16 v[92:93], v193 offset:0
	ds_read_b64_tr_b16 v[94:95], v193 offset:512
	ds_read_b64_tr_b16 v[100:101], v193 offset:4096
	ds_read_b64_tr_b16 v[102:103], v193 offset:4608
	v_mfma_f32_32x32x16_bf16 v[52:67], v[20:23], v[4:7], v[68:83]
	v_add_f32_e32 v221, v36, v37
	v_add_f32_e32 v221, v221, v38
	v_add_f32_e32 v221, v221, v39
	v_add_f32_e32 v221, v221, v40
	v_add_f32_e32 v221, v221, v41
	v_cvt_pk_bf16_f32 v84, v36, v37
	v_cvt_pk_bf16_f32 v85, v38, v39
	ds_read_b64_tr_b16 v[108:109], v193 offset:8192
	ds_read_b64_tr_b16 v[110:111], v193 offset:8704
	ds_read_b64_tr_b16 v[116:117], v193 offset:12288
	ds_read_b64_tr_b16 v[118:119], v193 offset:12800
	v_mfma_f32_32x32x16_bf16 v[52:67], v[24:27], v[8:11], v[52:67]
	v_add_f32_e32 v221, v221, v42
	v_add_f32_e32 v221, v221, v43
	v_add_f32_e32 v221, v221, v44
	v_add_f32_e32 v221, v221, v45
	v_cvt_pk_bf16_f32 v86, v40, v41
	v_cvt_pk_bf16_f32 v87, v42, v43
	ds_read_b64_tr_b16 v[96:97], v193 offset:1024
	ds_read_b64_tr_b16 v[98:99], v193 offset:1536
	ds_read_b64_tr_b16 v[104:105], v193 offset:5120
	ds_read_b64_tr_b16 v[106:107], v193 offset:5632
	v_mfma_f32_32x32x16_bf16 v[52:67], v[28:31], v[12:15], v[52:67]
	v_add_f32_e32 v221, v221, v46
	v_add_f32_e32 v221, v221, v47
	v_add_f32_e32 v221, v221, v48
	v_add_f32_e32 v221, v221, v49
	v_cvt_pk_bf16_f32 v88, v44, v45
	v_cvt_pk_bf16_f32 v89, v46, v47
	ds_read_b64_tr_b16 v[112:113], v193 offset:9216
	ds_read_b64_tr_b16 v[114:115], v193 offset:9728
	ds_read_b64_tr_b16 v[120:121], v193 offset:13312
	ds_read_b64_tr_b16 v[122:123], v193 offset:13824
	v_mfma_f32_32x32x16_bf16 v[52:67], v[32:35], v[16:19], v[52:67]
	v_add_f32_e32 v221, v221, v50
	v_add_f32_e32 v221, v221, v51
	v_cvt_pk_bf16_f32 v90, v48, v49
	v_cvt_pk_bf16_f32 v91, v50, v51
	v_add_f32_e32 v189, v189, v221
	s_nop 6
	v_max3_f32 v194, v52, v53, v54
	v_max3_f32 v195, v55, v56, v57
	v_max3_f32 v194, v194, v58, v59
	v_max3_f32 v195, v195, v60, v61
	v_max3_f32 v194, v194, v62, v63
	v_max3_f32 v195, v195, v64, v65
	v_max3_f32 v194, v194, v66, v67
	v_max_f32_e32 v190, v194, v195
	v_mov_b32_e32 v194, v190
	s_nop 1
	v_permlane32_swap_b32_e32 v190, v194
	v_max_f32_e32 v190, v190, v194
	s_mov_b32 s54, 0
	v_cmp_lt_f32_e32 vcc, s48, v190
	s_nop 0
	s_cmp_lg_u64 vcc, 0
	s_cbranch_scc0 .Lat_nores17
	v_max_f32_e32 v190, 0, v190
	v_add_f32_e32 v188, v188, v190
	v_sub_f32_e32 v52, v52, v190
	v_sub_f32_e32 v53, v53, v190
	v_sub_f32_e32 v54, v54, v190
	v_sub_f32_e32 v55, v55, v190
	v_sub_f32_e32 v56, v56, v190
	v_sub_f32_e32 v57, v57, v190
	v_sub_f32_e32 v58, v58, v190
	v_sub_f32_e32 v59, v59, v190
	v_sub_f32_e32 v60, v60, v190
	v_sub_f32_e32 v61, v61, v190
	v_sub_f32_e32 v62, v62, v190
	v_sub_f32_e32 v63, v63, v190
	v_sub_f32_e32 v64, v64, v190
	v_sub_f32_e32 v65, v65, v190
	v_sub_f32_e32 v66, v66, v190
	v_sub_f32_e32 v67, v67, v190
	v_xor_b32_e32 v68, 0x80000000, v188
	v_xor_b32_e32 v69, 0x80000000, v188
	v_xor_b32_e32 v70, 0x80000000, v188
	v_xor_b32_e32 v71, 0x80000000, v188
	v_xor_b32_e32 v72, 0x80000000, v188
	v_xor_b32_e32 v73, 0x80000000, v188
	v_xor_b32_e32 v74, 0x80000000, v188
	v_xor_b32_e32 v75, 0x80000000, v188
	v_xor_b32_e32 v76, 0x80000000, v188
	v_xor_b32_e32 v77, 0x80000000, v188
	v_xor_b32_e32 v78, 0x80000000, v188
	v_xor_b32_e32 v79, 0x80000000, v188
	v_xor_b32_e32 v80, 0x80000000, v188
	v_xor_b32_e32 v81, 0x80000000, v188
	v_xor_b32_e32 v82, 0x80000000, v188
	v_xor_b32_e32 v83, 0x80000000, v188
	v_exp_f32_e64 v191, -v190
	s_mov_b32 s54, 1
	v_add_u32_e32 v197, v210, v215
	v_mul_f32_e32 v189, v189, v191
	ds_write_b32 v197, v191 offset:0
; #define SBAR() __builtin_amdgcn_sched_barrier(0)
;   #define RESC() do{ if(resc){ asm volatile("s_waitcnt lgkmcnt(0)":::"memory"); \
;       _Pragma("unroll") for(int d_=0;d_<2;++d_) _Pragma("unroll") for(int r=0;r<16;++r)o[d_][r]*=wsf[crow(r,hi)]; } }while(0)
;   #define PKW(P,B) cvtpk_s(P[B],P[B+1])
; template<int THRL,bool PART> __device__ __forceinline__ int attn_unit(const bf16*Qb,const bf16*__restrict__ Kh,const bf16*__restrict__ Vh,bf16*Ob,const int NT,const int vlim_in,char*shm,const int s0,const bool primed,const bf16*nKh,const bf16*nVh,bf16*fuseM,const float lam){
;     ...
;   STEP(pB0,pB1,pA0,pA1,NT-1,false,false,false); RESC();
;   if(act){ float sacc=pB0[0]+pB0[1]; _Pragma("unroll") for(int r=2;r<16;++r)sacc+=pB0[r]; _Pragma("unroll") for(int r=0;r<16;++r)sacc+=pB1[r]; l_reg+=sacc;
;     pw0=(u32x4){PKW(pB0,0),PKW(pB0,2),PKW(pB0,4),PKW(pB0,6)};pw1=(u32x4){PKW(pB0,8),PKW(pB0,10),PKW(pB0,12),PKW(pB0,14)};pw2=(u32x4){PKW(pB1,0),PKW(pB1,2),PKW(pB1,4),PKW(pB1,6)};pw3=(u32x4){PKW(pB1,8),PKW(pB1,10),PKW(pB1,12),PKW(pB1,14)};
;     SBAR(); pv(o,vb0+sl_cur,PAF(0),PAF(1),PAF(2),PAF(3)); }
.Lat_nores17:
	v_add_u32_e32 v192, s26, v208
	s_waitcnt lgkmcnt(0)
	v_mfma_f32_32x32x16_bf16 v[124:139], v[84:87], v[92:95], v[124:139]
	v_exp_f32_e32 v52, v52
	v_exp_f32_e32 v53, v53
	v_mfma_f32_32x32x16_bf16 v[140:155], v[84:87], v[100:103], v[140:155]
	v_exp_f32_e32 v54, v54
	v_exp_f32_e32 v55, v55
	s_add_i32 s34, s17, 1
	s_cmp_lt_u32 s34, s16
	s_cbranch_scc0 .Lat_nokf18
	v_mfma_f32_32x32x16_bf16 v[156:171], v[84:87], v[108:111], v[156:171]
	v_exp_f32_e32 v56, v56
	v_exp_f32_e32 v57, v57
	ds_read_b128 v[20:23], v192 offset:0
	v_mfma_f32_32x32x16_bf16 v[172:187], v[84:87], v[116:119], v[172:187]
	v_exp_f32_e32 v58, v58
	v_exp_f32_e32 v59, v59
	ds_read_b128 v[24:27], v192 offset:2048
	v_mfma_f32_32x32x16_bf16 v[124:139], v[88:91], v[96:99], v[124:139]
	v_exp_f32_e32 v60, v60
	v_exp_f32_e32 v61, v61
	ds_read_b128 v[28:31], v192 offset:4096
	v_mfma_f32_32x32x16_bf16 v[140:155], v[88:91], v[104:107], v[140:155]
	v_exp_f32_e32 v62, v62
	v_exp_f32_e32 v63, v63
	ds_read_b128 v[32:35], v192 offset:6144
	v_mfma_f32_32x32x16_bf16 v[156:171], v[88:91], v[112:115], v[156:171]
	v_exp_f32_e32 v64, v64
	v_exp_f32_e32 v65, v65
	v_mfma_f32_32x32x16_bf16 v[172:187], v[88:91], v[120:123], v[172:187]
	v_exp_f32_e32 v66, v66
	v_exp_f32_e32 v67, v67
	s_branch .Lat_end16
.Lat_nokf18:
	v_mfma_f32_32x32x16_bf16 v[156:171], v[84:87], v[108:111], v[156:171]
	v_exp_f32_e32 v56, v56
	v_exp_f32_e32 v57, v57
	v_mfma_f32_32x32x16_bf16 v[172:187], v[84:87], v[116:119], v[172:187]
	v_exp_f32_e32 v58, v58
	v_exp_f32_e32 v59, v59
	v_mfma_f32_32x32x16_bf16 v[124:139], v[88:91], v[96:99], v[124:139]
	v_exp_f32_e32 v60, v60
	v_exp_f32_e32 v61, v61
	v_mfma_f32_32x32x16_bf16 v[140:155], v[88:91], v[104:107], v[140:155]
	v_exp_f32_e32 v62, v62
	v_exp_f32_e32 v63, v63
	v_mfma_f32_32x32x16_bf16 v[156:171], v[88:91], v[112:115], v[156:171]
	v_exp_f32_e32 v64, v64
	v_exp_f32_e32 v65, v65
	v_mfma_f32_32x32x16_bf16 v[172:187], v[88:91], v[120:123], v[172:187]
	v_exp_f32_e32 v66, v66
	v_exp_f32_e32 v67, v67
	s_branch .Lat_end16
.Lat_last15:
	s_mov_b32 s54, 0
	s_cmp_eq_u32 s17, s16
	s_cbranch_scc0 .Lat_end16
	v_add_u32_e32 v193, s28, v209
	ds_read_b64_tr_b16 v[92:93], v193 offset:0
	ds_read_b64_tr_b16 v[94:95], v193 offset:512
	ds_read_b64_tr_b16 v[100:101], v193 offset:4096
	ds_read_b64_tr_b16 v[102:103], v193 offset:4608
	v_add_f32_e32 v221, v36, v37
	v_add_f32_e32 v221, v221, v38
	v_add_f32_e32 v221, v221, v39
	v_add_f32_e32 v221, v221, v40
	v_add_f32_e32 v221, v221, v41
	v_cvt_pk_bf16_f32 v84, v36, v37
	v_cvt_pk_bf16_f32 v85, v38, v39
	ds_read_b64_tr_b16 v[108:109], v193 offset:8192
	ds_read_b64_tr_b16 v[110:111], v193 offset:8704
	ds_read_b64_tr_b16 v[116:117], v193 offset:12288
	ds_read_b64_tr_b16 v[118:119], v193 offset:12800
	v_add_f32_e32 v221, v221, v42
	v_add_f32_e32 v221, v221, v43
	v_add_f32_e32 v221, v221, v44
	v_add_f32_e32 v221, v221, v45
	v_cvt_pk_bf16_f32 v86, v40, v41
	v_cvt_pk_bf16_f32 v87, v42, v43
	ds_read_b64_tr_b16 v[96:97], v193 offset:1024
	ds_read_b64_tr_b16 v[98:99], v193 offset:1536
	ds_read_b64_tr_b16 v[104:105], v193 offset:5120
	ds_read_b64_tr_b16 v[106:107], v193 offset:5632
	v_add_f32_e32 v221, v221, v46
	v_add_f32_e32 v221, v221, v47
	v_add_f32_e32 v221, v221, v48
	v_add_f32_e32 v221, v221, v49
	v_cvt_pk_bf16_f32 v88, v44, v45
	v_cvt_pk_bf16_f32 v89, v46, v47
	ds_read_b64_tr_b16 v[112:113], v193 offset:9216
	ds_read_b64_tr_b16 v[114:115], v193 offset:9728
	ds_read_b64_tr_b16 v[120:121], v193 offset:13312
	ds_read_b64_tr_b16 v[122:123], v193 offset:13824
	v_add_f32_e32 v221, v221, v50
	v_add_f32_e32 v221, v221, v51
	v_cvt_pk_bf16_f32 v90, v48, v49
	v_cvt_pk_bf16_f32 v91, v50, v51
	v_add_f32_e32 v189, v189, v221
	s_waitcnt lgkmcnt(0)
	v_mfma_f32_32x32x16_bf16 v[124:139], v[84:87], v[92:95], v[124:139]
	v_mfma_f32_32x32x16_bf16 v[140:155], v[84:87], v[100:103], v[140:155]
	v_mfma_f32_32x32x16_bf16 v[156:171], v[84:87], v[108:111], v[156:171]
	v_mfma_f32_32x32x16_bf16 v[172:187], v[84:87], v[116:119], v[172:187]
	v_mfma_f32_32x32x16_bf16 v[124:139], v[88:91], v[96:99], v[124:139]
	v_mfma_f32_32x32x16_bf16 v[140:155], v[88:91], v[104:107], v[140:155]
	v_mfma_f32_32x32x16_bf16 v[156:171], v[88:91], v[112:115], v[156:171]
	v_mfma_f32_32x32x16_bf16 v[172:187], v[88:91], v[120:123], v[172:187]

; __device__ __forceinline__ int crow(int r,int hi){return (r&3)+8*(r>>2)+4*hi;}
; template<int THRL,bool PART> __device__ __forceinline__ int attn_unit(const bf16*Qb,const bf16*__restrict__ Kh,const bf16*__restrict__ Vh,bf16*Ob,const int NT,const int vlim_in,char*shm,const int s0,const bool primed,const bf16*nKh,const bf16*nVh,bf16*fuseM,const float lam){
;     ...
;   if(act){
;   {auto rr=__builtin_amdgcn_permlane32_swap(__float_as_uint(l_reg),__float_as_uint(l_reg),false,false);l_reg=__uint_as_float(rr[0])+__uint_as_float(rr[1]);}
;   if(hi==0)wsf[32+r32]=l_reg;asm volatile("s_waitcnt lgkmcnt(0)":::"memory");
;   float rli[16];
;   #pragma unroll
;   for(int r=0;r<16;++r)rli[r]=__builtin_amdgcn_rcpf(wsf[32+crow(r,hi)]);
.Lat_bar21:
	s_barrier
	s_add_i32 s24, s24, 1
	s_and_b32 s24, s24, 3
	s_add_i32 s17, s17, 1
	s_cmp_le_u32 s17, s15
	s_cbranch_scc1 .Lat_t2
.Lat_tx3:
	v_mov_b32_e32 v194, v189
	s_nop 1
	v_permlane32_swap_b32_e32 v189, v194
	v_add_f32_e32 v189, v189, v194
	s_cmp_eq_u32 s6, 0
	s_cbranch_scc1 .Lat_h023
	v_add_u32_e32 v197, v210, v215
	ds_write_b32 v197, v188 offset:128
	ds_write_b32 v197, v189 offset:256
	s_nop 7
	s_nop 3
	ds_write_b128 v222, v[124:127] offset:0
	ds_write_b128 v222, v[128:131] offset:1024
	ds_write_b128 v222, v[132:135] offset:2048
	ds_write_b128 v222, v[136:139] offset:3072
	ds_write_b128 v222, v[140:143] offset:4096
	ds_write_b128 v222, v[144:147] offset:5120
	ds_write_b128 v222, v[148:151] offset:6144
	ds_write_b128 v222, v[152:155] offset:7168
	ds_write_b128 v222, v[156:159] offset:8192
	ds_write_b128 v222, v[160:163] offset:9216
	ds_write_b128 v222, v[164:167] offset:10240
	ds_write_b128 v222, v[168:171] offset:11264
	ds_write_b128 v222, v[172:175] offset:12288
	ds_write_b128 v222, v[176:179] offset:13312
	ds_write_b128 v222, v[180:183] offset:14336
	ds_write_b128 v222, v[184:187] offset:15360
.Lat_h023:
	s_waitcnt lgkmcnt(0)
	s_barrier
	s_cmp_lg_u32 s6, 0
	s_cbranch_scc1 .Lat_mdone24
	v_add_u32_e32 v197, v210, v215
	ds_read_b32 v198, v197 offset:4224
	ds_read_b32 v199, v197 offset:4352
	s_waitcnt lgkmcnt(0)
	v_max_f32_e32 v200, v188, v198
	v_sub_f32_e32 v201, v188, v200
	v_sub_f32_e32 v202, v198, v200
	v_exp_f32_e32 v201, v201
	v_exp_f32_e32 v202, v202
	s_nop 0
	v_mul_f32_e32 v203, v189, v201
	v_fmac_f32_e32 v203, v199, v202
	v_rcp_f32_e32 v203, v203
	s_nop 0
	v_mul_f32_e32 v201, v201, v203
	v_mul_f32_e32 v202, v202, v203
	ds_write_b32 v197, v201 offset:384
	ds_write_b32 v197, v202 offset:512
	s_waitcnt lgkmcnt(0)
	v_add_u32_e32 v197, v210, v216
	ds_read_b128 v[92:95], v197 offset:384
	ds_read_b128 v[96:99], v197 offset:416
	ds_read_b128 v[100:103], v197 offset:448
	ds_read_b128 v[104:107], v197 offset:480
	v_add_u32_e32 v197, v210, v216
	ds_read_b128 v[108:111], v197 offset:512
	ds_read_b128 v[112:115], v197 offset:544
	ds_read_b128 v[116:119], v197 offset:576
	ds_read_b128 v[120:123], v197 offset:608
	ds_read_b128 v[20:23], v222 offset:0
	ds_read_b128 v[24:27], v222 offset:1024
	ds_read_b128 v[28:31], v222 offset:2048
	ds_read_b128 v[32:35], v222 offset:3072
	s_waitcnt lgkmcnt(0)
	v_mul_f32_e32 v124, v124, v92
	v_mul_f32_e32 v125, v125, v93
	v_mul_f32_e32 v126, v126, v94
	v_mul_f32_e32 v127, v127, v95
	v_mul_f32_e32 v128, v128, v96
	v_mul_f32_e32 v129, v129, v97
	v_mul_f32_e32 v130, v130, v98
	v_mul_f32_e32 v131, v131, v99
	v_mul_f32_e32 v132, v132, v100
	v_mul_f32_e32 v133, v133, v101
	v_mul_f32_e32 v134, v134, v102
	v_mul_f32_e32 v135, v135, v103
	v_mul_f32_e32 v136, v136, v104
	v_mul_f32_e32 v137, v137, v105
	v_mul_f32_e32 v138, v138, v106
	v_mul_f32_e32 v139, v139, v107
	v_fmac_f32_e32 v124, v20, v108
	v_fmac_f32_e32 v125, v21, v109
	v_fmac_f32_e32 v126, v22, v110
	v_fmac_f32_e32 v127, v23, v111
	v_fmac_f32_e32 v128, v24, v112
	v_fmac_f32_e32 v129, v25, v113
	v_fmac_f32_e32 v130, v26, v114
	v_fmac_f32_e32 v131, v27, v115
	v_fmac_f32_e32 v132, v28, v116
	v_fmac_f32_e32 v133, v29, v117
	v_fmac_f32_e32 v134, v30, v118
	v_fmac_f32_e32 v135, v31, v119
	v_fmac_f32_e32 v136, v32, v120
	v_fmac_f32_e32 v137, v33, v121
	v_fmac_f32_e32 v138, v34, v122
	v_fmac_f32_e32 v139, v35, v123
	ds_read_b128 v[20:23], v222 offset:4096
	ds_read_b128 v[24:27], v222 offset:5120
	ds_read_b128 v[28:31], v222 offset:6144
	ds_read_b128 v[32:35], v222 offset:7168
	s_waitcnt lgkmcnt(0)
	v_mul_f32_e32 v140, v140, v92
	v_mul_f32_e32 v141, v141, v93
	v_mul_f32_e32 v142, v142, v94
	v_mul_f32_e32 v143, v143, v95
	v_mul_f32_e32 v144, v144, v96
	v_mul_f32_e32 v145, v145, v97
	v_mul_f32_e32 v146, v146, v98
	v_mul_f32_e32 v147, v147, v99
	v_mul_f32_e32 v148, v148, v100
	v_mul_f32_e32 v149, v149, v101
	v_mul_f32_e32 v150, v150, v102
	v_mul_f32_e32 v151, v151, v103
	v_mul_f32_e32 v152, v152, v104
	v_mul_f32_e32 v153, v153, v105
	v_mul_f32_e32 v154, v154, v106
	v_mul_f32_e32 v155, v155, v107
	v_fmac_f32_e32 v140, v20, v108
	v_fmac_f32_e32 v141, v21, v109
	v_fmac_f32_e32 v142, v22, v110
	v_fmac_f32_e32 v143, v23, v111
	v_fmac_f32_e32 v144, v24, v112
	v_fmac_f32_e32 v145, v25, v113
	v_fmac_f32_e32 v146, v26, v114
	v_fmac_f32_e32 v147, v27, v115
	v_fmac_f32_e32 v148, v28, v116
	v_fmac_f32_e32 v149, v29, v117
	v_fmac_f32_e32 v150, v30, v118
	v_fmac_f32_e32 v151, v31, v119
	v_fmac_f32_e32 v152, v32, v120
	v_fmac_f32_e32 v153, v33, v121
	v_fmac_f32_e32 v154, v34, v122
	v_fmac_f32_e32 v155, v35, v123
	ds_read_b128 v[20:23], v222 offset:8192
	ds_read_b128 v[24:27], v222 offset:9216
	ds_read_b128 v[28:31], v222 offset:10240
	ds_read_b128 v[32:35], v222 offset:11264
	s_waitcnt lgkmcnt(0)
	v_mul_f32_e32 v156, v156, v92
	v_mul_f32_e32 v157, v157, v93
	v_mul_f32_e32 v158, v158, v94
	v_mul_f32_e32 v159, v159, v95
	v_mul_f32_e32 v160, v160, v96
	v_mul_f32_e32 v161, v161, v97
	v_mul_f32_e32 v162, v162, v98
	v_mul_f32_e32 v163, v163, v99
	v_mul_f32_e32 v164, v164, v100
	v_mul_f32_e32 v165, v165, v101
	v_mul_f32_e32 v166, v166, v102
	v_mul_f32_e32 v167, v167, v103
	v_mul_f32_e32 v168, v168, v104
	v_mul_f32_e32 v169, v169, v105
	v_mul_f32_e32 v170, v170, v106
	v_mul_f32_e32 v171, v171, v107
	v_fmac_f32_e32 v156, v20, v108
	v_fmac_f32_e32 v157, v21, v109
	v_fmac_f32_e32 v158, v22, v110
	v_fmac_f32_e32 v159, v23, v111
	v_fmac_f32_e32 v160, v24, v112
	v_fmac_f32_e32 v161, v25, v113
	v_fmac_f32_e32 v162, v26, v114
	v_fmac_f32_e32 v163, v27, v115
	v_fmac_f32_e32 v164, v28, v116
	v_fmac_f32_e32 v165, v29, v117
	v_fmac_f32_e32 v166, v30, v118
	v_fmac_f32_e32 v167, v31, v119
	v_fmac_f32_e32 v168, v32, v120
	v_fmac_f32_e32 v169, v33, v121
	v_fmac_f32_e32 v170, v34, v122
	v_fmac_f32_e32 v171, v35, v123
	ds_read_b128 v[20:23], v222 offset:12288
	ds_read_b128 v[24:27], v222 offset:13312
	ds_read_b128 v[28:31], v222 offset:14336
	ds_read_b128 v[32:35], v222 offset:15360
	s_waitcnt lgkmcnt(0)
	v_mul_f32_e32 v172, v172, v92
	v_mul_f32_e32 v173, v173, v93
	v_mul_f32_e32 v174, v174, v94
	v_mul_f32_e32 v175, v175, v95
	v_mul_f32_e32 v176, v176, v96
	v_mul_f32_e32 v177, v177, v97
	v_mul_f32_e32 v178, v178, v98
	v_mul_f32_e32 v179, v179, v99
	v_mul_f32_e32 v180, v180, v100
	v_mul_f32_e32 v181, v181, v101
	v_mul_f32_e32 v182, v182, v102
	v_mul_f32_e32 v183, v183, v103
	v_mul_f32_e32 v184, v184, v104
	v_mul_f32_e32 v185, v185, v105
	v_mul_f32_e32 v186, v186, v106
	v_mul_f32_e32 v187, v187, v107
	v_fmac_f32_e32 v172, v20, v108
	v_fmac_f32_e32 v173, v21, v109
	v_fmac_f32_e32 v174, v22, v110
	v_fmac_f32_e32 v175, v23, v111
	v_fmac_f32_e32 v176, v24, v112
	v_fmac_f32_e32 v177, v25, v113
	v_fmac_f32_e32 v178, v26, v114
	v_fmac_f32_e32 v179, v27, v115
	v_fmac_f32_e32 v180, v28, v116
	v_fmac_f32_e32 v181, v29, v117
	v_fmac_f32_e32 v182, v30, v118
	v_fmac_f32_e32 v183, v31, v119
	v_fmac_f32_e32 v184, v32, v120
	v_fmac_f32_e32 v185, v33, v121
	v_fmac_f32_e32 v186, v34, v122
	v_fmac_f32_e32 v187, v35, v123
; template<int THRL,bool PART> __device__ __forceinline__ int attn_unit(const bf16*Qb,const bf16*__restrict__ Kh,const bf16*__restrict__ Vh,bf16*Ob,const int NT,const int vlim_in,char*shm,const int s0,const bool primed,const bf16*nKh,const bf16*nVh,bf16*fuseM,const float lam){
;     ...
;     if(!fuseM){
;     #pragma unroll
;     for(int i=0;i<4;++i){const int row=i*8+(lane>>3),ch=lane&7; const u32x4 v=*(const u32x4*)(stg+row*64+ch*8); ATTN_STORE16(Ow+(long)row*OP+ch*8,v);}
;     } else {
;     asm volatile("s_waitcnt vmcnt(0)":::"memory"); __builtin_amdgcn_fence(__ATOMIC_ACQUIRE,"agent");
;     bf16*Mw=fuseM+(long)(wid*QBLK)*OP;
;     #pragma unroll
;     for(int i=0;i<4;++i){const int row=i*8+(lane>>3),ch=lane&7; const u32x4 v=*(const u32x4*)(stg+row*64+ch*8);
;       const bf16*gp=Ow+(long)row*OP+ch*8; const u32x4 a=*(const u32x4*)(gp-192), c1=*(const u32x4*)(gp-128), b=*(const u32x4*)(gp-64);
;       float d0[8],d1[8],ss=0.f;
;       #pragma unroll
;       for(int q=0;q<4;++q){ d0[2*q]=__uint_as_float(a[q]<<16)-lam*__uint_as_float(b[q]<<16); d0[2*q+1]=__uint_as_float(a[q]&0xffff0000u)-lam*__uint_as_float(b[q]&0xffff0000u);
;         d1[2*q]=__uint_as_float(c1[q]<<16)-lam*__uint_as_float(v[q]<<16); d1[2*q+1]=__uint_as_float(c1[q]&0xffff0000u)-lam*__uint_as_float(v[q]&0xffff0000u);
;         ss+=d0[2*q]*d0[2*q]+d0[2*q+1]*d0[2*q+1]+d1[2*q]*d1[2*q]+d1[2*q+1]*d1[2*q+1]; }
.Lat_mdone24:
	s_barrier
	s_cmp_lg_u32 s14, 0
	s_cbranch_scc1 .Lat_comb25
	s_cmp_lg_u32 s6, 0
	s_cbranch_scc1 .Lat_udone26
	global_store_dwordx4 v217, v[124:127], s[52:53]
	global_store_dwordx4 v217, v[128:131], s[52:53] offset:1024
	global_store_dwordx4 v217, v[132:135], s[52:53] offset:2048
	global_store_dwordx4 v217, v[136:139], s[52:53] offset:3072
	global_store_dwordx4 v218, v[140:143], s[52:53]
	global_store_dwordx4 v218, v[144:147], s[52:53] offset:1024
	global_store_dwordx4 v218, v[148:151], s[52:53] offset:2048
	global_store_dwordx4 v218, v[152:155], s[52:53] offset:3072
	global_store_dwordx4 v219, v[156:159], s[52:53]
	global_store_dwordx4 v219, v[160:163], s[52:53] offset:1024
	global_store_dwordx4 v219, v[164:167], s[52:53] offset:2048
	global_store_dwordx4 v219, v[168:171], s[52:53] offset:3072
	global_store_dwordx4 v220, v[172:175], s[52:53]
	global_store_dwordx4 v220, v[176:179], s[52:53] offset:1024
	global_store_dwordx4 v220, v[180:183], s[52:53] offset:2048
	global_store_dwordx4 v220, v[184:187], s[52:53] offset:3072
	s_branch .Lat_udone26
.Lat_comb25:
	s_cmp_lg_u32 s6, 0
	s_cbranch_scc1 .Lat_skipst27
	global_load_dwordx4 v[20:23], v217, s[52:53] sc1
	global_load_dwordx4 v[24:27], v217, s[52:53] offset:1024 sc1
	global_load_dwordx4 v[28:31], v217, s[52:53] offset:2048 sc1
	global_load_dwordx4 v[32:35], v217, s[52:53] offset:3072 sc1
	global_load_dwordx4 v[36:39], v218, s[52:53] sc1
	global_load_dwordx4 v[40:43], v218, s[52:53] offset:1024 sc1
	global_load_dwordx4 v[44:47], v218, s[52:53] offset:2048 sc1
	global_load_dwordx4 v[48:51], v218, s[52:53] offset:3072 sc1
	global_load_dwordx4 v[52:55], v219, s[52:53] sc1
	global_load_dwordx4 v[56:59], v219, s[52:53] offset:1024 sc1
	global_load_dwordx4 v[60:63], v219, s[52:53] offset:2048 sc1
	global_load_dwordx4 v[64:67], v219, s[52:53] offset:3072 sc1
	global_load_dwordx4 v[68:71], v220, s[52:53] sc1
	global_load_dwordx4 v[72:75], v220, s[52:53] offset:1024 sc1
	global_load_dwordx4 v[76:79], v220, s[52:53] offset:2048 sc1
	global_load_dwordx4 v[80:83], v220, s[52:53] offset:3072 sc1
	v_mov_b32_e32 v194, s7
	s_mul_i32 s34, s5, 0x4200
	v_mul_u32_u24_e32 v197, 0x840, v2
	v_add_u32_e32 v197, v197, v215
	v_add_u32_e32 v197, s34, v197
	s_waitcnt vmcnt(0)
	v_fma_f32 v20, -v194, v124, v20
	v_fma_f32 v21, -v194, v125, v21
	v_fma_f32 v22, -v194, v126, v22
	v_fma_f32 v23, -v194, v127, v23
	v_fma_f32 v24, -v194, v128, v24
	v_fma_f32 v25, -v194, v129, v25
	v_fma_f32 v26, -v194, v130, v26
	v_fma_f32 v27, -v194, v131, v27
	v_fma_f32 v28, -v194, v132, v28
	v_fma_f32 v29, -v194, v133, v29
	v_fma_f32 v30, -v194, v134, v30
	v_fma_f32 v31, -v194, v135, v31
	v_fma_f32 v32, -v194, v136, v32
	v_fma_f32 v33, -v194, v137, v33
	v_fma_f32 v34, -v194, v138, v34
	v_fma_f32 v35, -v194, v139, v35
	v_fma_f32 v36, -v194, v140, v36
	v_fma_f32 v37, -v194, v141, v37
	v_fma_f32 v38, -v194, v142, v38
	v_fma_f32 v39, -v194, v143, v39
	v_fma_f32 v40, -v194, v144, v40
	v_fma_f32 v41, -v194, v145, v41
	v_fma_f32 v42, -v194, v146, v42
	v_fma_f32 v43, -v194, v147, v43
	v_fma_f32 v44, -v194, v148, v44
	v_fma_f32 v45, -v194, v149, v45
	v_fma_f32 v46, -v194, v150, v46
	v_fma_f32 v47, -v194, v151, v47
	v_fma_f32 v48, -v194, v152, v48
	v_fma_f32 v49, -v194, v153, v49
	v_fma_f32 v50, -v194, v154, v50
	v_fma_f32 v51, -v194, v155, v51
	v_fma_f32 v52, -v194, v156, v52
	v_fma_f32 v53, -v194, v157, v53
	v_fma_f32 v54, -v194, v158, v54
	v_fma_f32 v55, -v194, v159, v55
	v_fma_f32 v56, -v194, v160, v56
	v_fma_f32 v57, -v194, v161, v57
	v_fma_f32 v58, -v194, v162, v58
	v_fma_f32 v59, -v194, v163, v59
	v_fma_f32 v60, -v194, v164, v60
	v_fma_f32 v61, -v194, v165, v61
	v_fma_f32 v62, -v194, v166, v62
	v_fma_f32 v63, -v194, v167, v63
	v_fma_f32 v64, -v194, v168, v64
	v_fma_f32 v65, -v194, v169, v65
	v_fma_f32 v66, -v194, v170, v66
	v_fma_f32 v67, -v194, v171, v67
	v_fma_f32 v68, -v194, v172, v68
	v_fma_f32 v69, -v194, v173, v69
	v_fma_f32 v70, -v194, v174, v70
	v_fma_f32 v71, -v194, v175, v71
	v_fma_f32 v72, -v194, v176, v72
	v_fma_f32 v73, -v194, v177, v73
	v_fma_f32 v74, -v194, v178, v74
	v_fma_f32 v75, -v194, v179, v75
	v_fma_f32 v76, -v194, v180, v76
	v_fma_f32 v77, -v194, v181, v77
	v_fma_f32 v78, -v194, v182, v78
	v_fma_f32 v79, -v194, v183, v79
	v_fma_f32 v80, -v194, v184, v80
	v_fma_f32 v81, -v194, v185, v81
	v_fma_f32 v82, -v194, v186, v82
	v_fma_f32 v83, -v194, v187, v83
	ds_write_b32 v197, v20 offset:0
	ds_write_b32 v197, v21 offset:528
	ds_write_b32 v197, v22 offset:1056
	ds_write_b32 v197, v23 offset:1584
	ds_write_b32 v197, v24 offset:4224
	ds_write_b32 v197, v25 offset:4752
	ds_write_b32 v197, v26 offset:5280
	ds_write_b32 v197, v27 offset:5808
	ds_write_b32 v197, v28 offset:8448
	ds_write_b32 v197, v29 offset:8976
	ds_write_b32 v197, v30 offset:9504
	ds_write_b32 v197, v31 offset:10032
	ds_write_b32 v197, v32 offset:12672
	ds_write_b32 v197, v33 offset:13200
	ds_write_b32 v197, v34 offset:13728
	ds_write_b32 v197, v35 offset:14256
	ds_write_b32 v197, v36 offset:128
	ds_write_b32 v197, v37 offset:656
	ds_write_b32 v197, v38 offset:1184
	ds_write_b32 v197, v39 offset:1712
	ds_write_b32 v197, v40 offset:4352
	ds_write_b32 v197, v41 offset:4880
	ds_write_b32 v197, v42 offset:5408
	ds_write_b32 v197, v43 offset:5936
	ds_write_b32 v197, v44 offset:8576
	ds_write_b32 v197, v45 offset:9104
	ds_write_b32 v197, v46 offset:9632
	ds_write_b32 v197, v47 offset:10160
	ds_write_b32 v197, v48 offset:12800
	ds_write_b32 v197, v49 offset:13328
	ds_write_b32 v197, v50 offset:13856
	ds_write_b32 v197, v51 offset:14384
	ds_write_b32 v197, v52 offset:256
	ds_write_b32 v197, v53 offset:784
	ds_write_b32 v197, v54 offset:1312
	ds_write_b32 v197, v55 offset:1840
	ds_write_b32 v197, v56 offset:4480
	ds_write_b32 v197, v57 offset:5008
	ds_write_b32 v197, v58 offset:5536
	ds_write_b32 v197, v59 offset:6064
	ds_write_b32 v197, v60 offset:8704
	ds_write_b32 v197, v61 offset:9232
	ds_write_b32 v197, v62 offset:9760
	ds_write_b32 v197, v63 offset:10288
	ds_write_b32 v197, v64 offset:12928
	ds_write_b32 v197, v65 offset:13456
	ds_write_b32 v197, v66 offset:13984
	ds_write_b32 v197, v67 offset:14512
	ds_write_b32 v197, v68 offset:384
	ds_write_b32 v197, v69 offset:912
	ds_write_b32 v197, v70 offset:1440
	ds_write_b32 v197, v71 offset:1968
	ds_write_b32 v197, v72 offset:4608
	ds_write_b32 v197, v73 offset:5136
	ds_write_b32 v197, v74 offset:5664
	ds_write_b32 v197, v75 offset:6192
	ds_write_b32 v197, v76 offset:8832
	ds_write_b32 v197, v77 offset:9360
	ds_write_b32 v197, v78 offset:9888
	ds_write_b32 v197, v79 offset:10416
	ds_write_b32 v197, v80 offset:13056
	ds_write_b32 v197, v81 offset:13584
	ds_write_b32 v197, v82 offset:14112
	ds_write_b32 v197, v83 offset:14640
; __device__ __forceinline__ unsigned cvtpk_s(float lo,float hi){f32x2_t v={lo,hi};bf16x2_t b=__builtin_convertvector(v,bf16x2_t);return __builtin_bit_cast(unsigned,b);}
; template<int THRL,bool PART> __device__ __forceinline__ int attn_unit(const bf16*Qb,const bf16*__restrict__ Kh,const bf16*__restrict__ Vh,bf16*Ob,const int NT,const int vlim_in,char*shm,const int s0,const bool primed,const bf16*nKh,const bf16*nVh,bf16*fuseM,const float lam){
;     ...
;       ss+=__shfl_xor(ss,1); ss+=__shfl_xor(ss,2); ss+=__shfl_xor(ss,4);
;       const float rn=rsqrtf(ss*(1.0f/128.0f)+1e-6f)*0.8f;
;       u32x4 w0,w1;
;       #pragma unroll
;       for(int q=0;q<4;++q){ w0[q]=cvtpk_s(d0[2*q]*rn,d0[2*q+1]*rn); w1[q]=cvtpk_s(d1[2*q]*rn,d1[2*q+1]*rn); }
;       *(u32x4*)(Mw+(long)row*OP+ch*8)=w0; *(u32x4*)(Mw+(long)row*OP+64+ch*8)=w1; }
.Lat_skipst27:
	s_waitcnt lgkmcnt(0)
	s_barrier
	v_lshrrev_b32_e32 v198, 2, v252
	v_and_b32_e32 v199, 3, v252
	v_mul_u32_u24_e32 v197, 0x210, v198
	v_lshl_add_u32 v197, v199, 7, v197
	ds_read_b128 v[36:39], v197 offset:0
	ds_read_b128 v[40:43], v197 offset:16
	ds_read_b128 v[44:47], v197 offset:32
	ds_read_b128 v[48:51], v197 offset:48
	ds_read_b128 v[52:55], v197 offset:64
	ds_read_b128 v[56:59], v197 offset:80
	ds_read_b128 v[60:63], v197 offset:96
	ds_read_b128 v[64:67], v197 offset:112
	s_waitcnt lgkmcnt(0)
	v_mul_f32_e32 v194, v36, v36
	v_fmac_f32_e32 v194, v37, v37
	v_fmac_f32_e32 v194, v38, v38
	v_fmac_f32_e32 v194, v39, v39
	v_fmac_f32_e32 v194, v40, v40
	v_fmac_f32_e32 v194, v41, v41
	v_fmac_f32_e32 v194, v42, v42
	v_fmac_f32_e32 v194, v43, v43
	v_fmac_f32_e32 v194, v44, v44
	v_fmac_f32_e32 v194, v45, v45
	v_fmac_f32_e32 v194, v46, v46
	v_fmac_f32_e32 v194, v47, v47
	v_fmac_f32_e32 v194, v48, v48
	v_fmac_f32_e32 v194, v49, v49
	v_fmac_f32_e32 v194, v50, v50
	v_fmac_f32_e32 v194, v51, v51
	v_fmac_f32_e32 v194, v52, v52
	v_fmac_f32_e32 v194, v53, v53
	v_fmac_f32_e32 v194, v54, v54
	v_fmac_f32_e32 v194, v55, v55
	v_fmac_f32_e32 v194, v56, v56
	v_fmac_f32_e32 v194, v57, v57
	v_fmac_f32_e32 v194, v58, v58
	v_fmac_f32_e32 v194, v59, v59
	v_fmac_f32_e32 v194, v60, v60
	v_fmac_f32_e32 v194, v61, v61
	v_fmac_f32_e32 v194, v62, v62
	v_fmac_f32_e32 v194, v63, v63
	v_fmac_f32_e32 v194, v64, v64
	v_fmac_f32_e32 v194, v65, v65
	v_fmac_f32_e32 v194, v66, v66
	v_fmac_f32_e32 v194, v67, v67
	s_nop 1
	v_add_f32_dpp v194, v194, v194 quad_perm:[1,0,3,2] row_mask:0xf bank_mask:0xf
	s_nop 1
	v_add_f32_dpp v194, v194, v194 quad_perm:[2,3,0,1] row_mask:0xf bank_mask:0xf
	v_mov_b32_e32 v195, 0x358637bd
	v_fmamk_f32 v194, v194, 0x3c000000, v195
	v_rsq_f32_e32 v194, v194
	s_nop 0
	v_mul_f32_e32 v194, 0x3f4ccccd, v194
	v_mul_f32_e32 v36, v36, v194
	v_mul_f32_e32 v37, v37, v194
	v_mul_f32_e32 v38, v38, v194
	v_mul_f32_e32 v39, v39, v194
	v_mul_f32_e32 v40, v40, v194
	v_mul_f32_e32 v41, v41, v194
	v_mul_f32_e32 v42, v42, v194
	v_mul_f32_e32 v43, v43, v194
	v_mul_f32_e32 v44, v44, v194
	v_mul_f32_e32 v45, v45, v194
	v_mul_f32_e32 v46, v46, v194
	v_mul_f32_e32 v47, v47, v194
	v_mul_f32_e32 v48, v48, v194
	v_mul_f32_e32 v49, v49, v194
	v_mul_f32_e32 v50, v50, v194
	v_mul_f32_e32 v51, v51, v194
	v_mul_f32_e32 v52, v52, v194
	v_mul_f32_e32 v53, v53, v194
	v_mul_f32_e32 v54, v54, v194
	v_mul_f32_e32 v55, v55, v194
	v_mul_f32_e32 v56, v56, v194
	v_mul_f32_e32 v57, v57, v194
	v_mul_f32_e32 v58, v58, v194
	v_mul_f32_e32 v59, v59, v194
	v_mul_f32_e32 v60, v60, v194
	v_mul_f32_e32 v61, v61, v194
	v_mul_f32_e32 v62, v62, v194
	v_mul_f32_e32 v63, v63, v194
	v_mul_f32_e32 v64, v64, v194
	v_mul_f32_e32 v65, v65, v194
	v_mul_f32_e32 v66, v66, v194
	v_mul_f32_e32 v67, v67, v194
	v_cvt_pk_bf16_f32 v20, v36, v37
	v_cvt_pk_bf16_f32 v21, v38, v39
	v_cvt_pk_bf16_f32 v22, v40, v41
	v_cvt_pk_bf16_f32 v23, v42, v43
	v_cvt_pk_bf16_f32 v24, v44, v45
	v_cvt_pk_bf16_f32 v25, v46, v47
	v_cvt_pk_bf16_f32 v26, v48, v49
	v_cvt_pk_bf16_f32 v27, v50, v51
	v_cvt_pk_bf16_f32 v28, v52, v53
	v_cvt_pk_bf16_f32 v29, v54, v55
	v_cvt_pk_bf16_f32 v30, v56, v57
	v_cvt_pk_bf16_f32 v31, v58, v59
	v_cvt_pk_bf16_f32 v32, v60, v61
	v_cvt_pk_bf16_f32 v33, v62, v63
	v_cvt_pk_bf16_f32 v34, v64, v65
	v_cvt_pk_bf16_f32 v35, v66, v67
	s_add_u32 s50, s66, 0x2e00400
	s_addc_u32 s51, s67, 0
	s_lshl_b32 s36, s9, 23
	s_add_u32 s50, s50, s36
	s_addc_u32 s51, s51, 0
	s_lshl_b32 s36, s13, 18
	s_add_u32 s50, s50, s36
	s_addc_u32 s51, s51, 0
	s_lshl_b32 s36, s10, 8
	s_add_u32 s50, s50, s36
	s_addc_u32 s51, s51, 0
	v_lshlrev_b32_e32 v197, 11, v198
	v_lshl_add_u32 v197, v199, 6, v197
	global_store_dwordx4 v197, v[20:23], s[50:51]
	global_store_dwordx4 v197, v[24:27], s[50:51] offset:16
	global_store_dwordx4 v197, v[28:31], s[50:51] offset:32
	global_store_dwordx4 v197, v[32:35], s[50:51] offset:48
